# top-k selected-bit record: the exec-masked block replaced by plain VALU selects with independent mask registers (no saveexec, branch or s_nop pads); on top of version 48
# baseline (speedup 1.0000x reference)
.LBB0_1403:
	v_max_f32_e32 v36, v93, v93
	v_cmp_lt_f32_e32 vcc, -2.0, v93
	v_max_f32_e32 v36, -2.0, v36
	v_mov_b32_e32 v42, 0
	v_max_f32_e32 v37, v56, v56
	v_cndmask_b32_e32 v35, v174, v92, vcc
	v_mov_b32_e32 v252, v54
	v_cmp_gt_f32_e32 vcc, v95, v36
	v_cmp_gt_f32_e64 s[8:9], v57, v37
	v_max_f32_e32 v36, v36, v95
	v_max_f32_e32 v37, v37, v57
	v_cndmask_b32_e32 v35, v35, v94, vcc
	v_cndmask_b32_e64 v252, v252, v55, s[8:9]
	v_cmp_gt_f32_e32 vcc, v64, v36
	v_cmp_gt_f32_e64 s[8:9], v48, v37
	v_max_f32_e32 v36, v36, v64
	v_max_f32_e32 v37, v37, v48
	v_cndmask_b32_e32 v35, v35, v62, vcc
	v_cndmask_b32_e64 v252, v252, v46, s[8:9]
	v_cmp_gt_f32_e32 vcc, v63, v36
	v_cmp_gt_f32_e64 s[8:9], v49, v37
	v_max_f32_e32 v36, v36, v63
	v_max_f32_e32 v37, v37, v49
	v_cndmask_b32_e32 v35, v35, v1, vcc
	v_cndmask_b32_e64 v252, v252, v47, s[8:9]
	v_cmp_gt_f32_e32 vcc, v76, v36
	v_cmp_gt_f32_e64 s[8:9], v40, v37
	v_max_f32_e32 v36, v36, v76
	v_max_f32_e32 v37, v37, v40
	v_cndmask_b32_e32 v35, v35, v66, vcc
	v_cndmask_b32_e64 v252, v252, v38, s[8:9]
	v_cmp_gt_f32_e32 vcc, v67, v36
	v_cmp_gt_f32_e64 s[8:9], v41, v37
	v_max_f32_e32 v36, v36, v67
	v_max_f32_e32 v37, v37, v41
	v_cndmask_b32_e32 v35, v35, v65, vcc
	v_cndmask_b32_e64 v252, v252, v39, s[8:9]
	v_cmp_gt_f32_e32 vcc, v70, v36
	v_cmp_gt_f32_e64 s[8:9], v32, v37
	v_max_f32_e32 v36, v36, v70
	v_max_f32_e32 v37, v37, v32
	v_cndmask_b32_e32 v35, v35, v68, vcc
	v_cndmask_b32_e64 v252, v252, v30, s[8:9]
	v_cmp_gt_f32_e32 vcc, v71, v36
	v_cmp_gt_f32_e64 s[8:9], v33, v37
	v_max_f32_e32 v36, v36, v71
	v_max_f32_e32 v37, v37, v33
	v_cndmask_b32_e32 v35, v35, v69, vcc
	v_cndmask_b32_e64 v252, v252, v31, s[8:9]
	v_cmp_gt_f32_e32 vcc, v37, v36
	v_max_f32_e32 v253, v36, v37
	s_nop 0
	v_cndmask_b32_e32 v36, v35, v252, vcc
	v_mov_b32_e32 v35, v253
	v_mov_b32_e32 v37, 0
	v_mov_b32_dpp v42, v36 row_ror:8 row_mask:0xf bank_mask:0xf
	s_nop 0
	v_mov_b32_dpp v37, v35 row_ror:8 row_mask:0xf bank_mask:0xf
	v_cmp_lt_f32_e64 s[12:13], v35, v37
	v_cmp_eq_f32_e32 vcc, v35, v37
	v_cmp_lt_i32_e64 s[8:9], v42, v36
	s_and_b64 s[8:9], vcc, s[8:9]
	s_or_b64 s[12:13], s[12:13], s[8:9]
	v_cndmask_b32_e64 v35, v35, v37, s[12:13]
	v_cndmask_b32_e64 v36, v36, v42, s[12:13]
	v_mov_b32_e32 v37, v35
	s_nop 1
	v_permlane16_swap_b32_e32 v35, v37
	v_mov_b32_e32 v42, v36
	s_nop 1
	v_permlane16_swap_b32_e32 v36, v42
	v_cmp_gt_f32_e64 s[8:9], v37, v35
	v_cmp_eq_f32_e32 vcc, v37, v35
	v_cmp_lt_i32_e64 s[12:13], v42, v36
	s_and_b64 s[12:13], vcc, s[12:13]
	s_or_b64 s[8:9], s[8:9], s[12:13]
	v_cndmask_b32_e64 v37, v35, v37, s[8:9]
	v_cndmask_b32_e64 v36, v36, v42, s[8:9]
	v_mov_b32_e32 v42, v37
	s_nop 1
	v_permlane32_swap_b32_e32 v37, v42
	v_mov_b32_e32 v35, v36
	s_nop 1
	v_permlane32_swap_b32_e32 v36, v35
	v_cmp_gt_f32_e64 s[14:15], v42, v37
	v_cmp_eq_f32_e32 vcc, v42, v37
	v_cmp_lt_i32_e64 s[8:9], v35, v36
	s_and_b64 s[8:9], vcc, s[8:9]
	s_or_b64 s[14:15], s[14:15], s[8:9]
	v_cndmask_b32_e64 v37, v37, v42, s[14:15]
	v_cmp_le_f32_e32 vcc, 0, v37
	s_cmp_eq_u64 vcc, 0
	s_cselect_b64 s[12:13], -1, 0
	s_cbranch_vccz .LBB0_1415
	v_cmp_lt_u32_e64 s[8:9], s7, v34
	v_cndmask_b32_e64 v35, v36, v35, s[14:15]
	s_and_b64 s[14:15], s[8:9], vcc
	v_bfe_u32 v37, v35, 5, 2
	v_lshlrev_b32_e64 v36, v35, 1
	v_cmp_eq_u32_e64 s[8:9], 0, v37
	v_cmp_eq_u32_e64 s[98:99], 1, v37
	v_cndmask_b32_e64 v36, 0, v36, s[14:15]
	v_cmp_eq_u32_e32 vcc, 2, v37
	v_cmp_eq_u32_e64 s[14:15], 3, v37
	v_cndmask_b32_e64 v42, 0, v36, s[8:9]
	v_or_b32_e32 v26, v42, v26
	v_cndmask_b32_e64 v42, 0, v36, s[98:99]
	v_or_b32_e32 v27, v42, v27
	v_cndmask_b32_e32 v42, 0, v36, vcc
	v_or_b32_e32 v28, v42, v28
	v_cndmask_b32_e64 v42, 0, v36, s[14:15]
	v_or_b32_e32 v29, v42, v29
.LBB0_1414:
	v_cmp_ne_u32_e64 s[8:9], v92, v35
	v_cmp_ne_u32_e64 s[14:15], v94, v35
	v_cmp_ne_u32_e64 s[98:99], v1, v35
	v_cmp_ne_u32_e32 vcc, v62, v35
	v_cndmask_b32_e64 v93, -2.0, v93, s[8:9]
	v_cndmask_b32_e64 v95, -2.0, v95, s[14:15]
	v_cndmask_b32_e64 v63, -2.0, v63, s[98:99]
	v_cndmask_b32_e32 v64, -2.0, v64, vcc
	v_cmp_ne_u32_e64 s[8:9], v65, v35
	v_cmp_ne_u32_e64 s[14:15], v66, v35
	v_cmp_ne_u32_e64 s[98:99], v69, v35
	v_cmp_ne_u32_e32 vcc, v68, v35
	v_cndmask_b32_e64 v67, -2.0, v67, s[8:9]
	v_cndmask_b32_e64 v76, -2.0, v76, s[14:15]
	v_cndmask_b32_e64 v71, -2.0, v71, s[98:99]
	v_cndmask_b32_e32 v70, -2.0, v70, vcc
	v_cmp_ne_u32_e64 s[8:9], v55, v35
	v_cmp_ne_u32_e64 s[14:15], v54, v35
	v_cmp_ne_u32_e64 s[98:99], v47, v35
	v_cmp_ne_u32_e32 vcc, v46, v35
	v_cndmask_b32_e64 v57, -2.0, v57, s[8:9]
	v_cndmask_b32_e64 v56, -2.0, v56, s[14:15]
	v_cndmask_b32_e64 v49, -2.0, v49, s[98:99]
	v_cndmask_b32_e32 v48, -2.0, v48, vcc
	v_cmp_ne_u32_e64 s[8:9], v39, v35
	v_cmp_ne_u32_e64 s[14:15], v38, v35
	v_cmp_ne_u32_e64 s[98:99], v31, v35
	v_cmp_ne_u32_e32 vcc, v30, v35
	v_cndmask_b32_e64 v41, -2.0, v41, s[8:9]
	v_cndmask_b32_e64 v40, -2.0, v40, s[14:15]
	v_cndmask_b32_e64 v33, -2.0, v33, s[98:99]
	v_cndmask_b32_e32 v32, -2.0, v32, vcc
